# stack + non-temporal store for the MoBA per-row lse values
# speedup vs baseline: 1.0109x; 1.0109x over previous
.LBB0_404:
	ds_bpermute_b32 v32, v238, v162
	v_add_u32_e32 v241, 0x100, v241
	v_add_u32_e32 v240, 0x100, v240
	s_waitcnt lgkmcnt(0)
	v_add_f32_e32 v33, v162, v32
	v_div_scale_f32 v34, s[0:1], v33, v33, 1.0
	v_rcp_f32_e32 v35, v34
	v_div_scale_f32 v36, vcc, 1.0, v33, 1.0
	v_lshrrev_b32_e32 v32, 13, v195
	v_fma_f32 v37, -v34, v35, 1.0
	v_fmac_f32_e32 v35, v37, v35
	v_mul_f32_e32 v37, v36, v35
	v_fma_f32 v38, -v34, v37, v36
	v_fmac_f32_e32 v37, v38, v35
	v_fma_f32 v34, -v34, v37, v36
	v_div_fmas_f32 v34, v34, v35, v37
	v_div_fixup_f32 v34, v34, v33, 1.0
	v_mul_f32_e32 v34, 0x41800000, v34
	v_mul_f32_e32 v0, v0, v34
	v_mul_f32_e32 v1, v1, v34
	v_mul_f32_e32 v16, v16, v34
	v_mul_f32_e32 v17, v17, v34
	v_mul_f32_e32 v2, v2, v34
	v_mul_f32_e32 v18, v18, v34
	v_mul_f32_e32 v3, v3, v34
	v_mul_f32_e32 v19, v19, v34
	v_mul_f32_e32 v4, v4, v34
	v_mul_f32_e32 v20, v20, v34
	v_mul_f32_e32 v5, v5, v34
	v_mul_f32_e32 v21, v21, v34
	v_mul_f32_e32 v6, v6, v34
	v_mul_f32_e32 v22, v22, v34
	v_mul_f32_e32 v7, v7, v34
	v_mul_f32_e32 v23, v23, v34
	v_mul_f32_e32 v8, v8, v34
	v_mul_f32_e32 v24, v24, v34
	v_mul_f32_e32 v9, v9, v34
	v_mul_f32_e32 v25, v25, v34
	v_mul_f32_e32 v10, v10, v34
	v_mul_f32_e32 v26, v26, v34
	v_mul_f32_e32 v11, v11, v34
	v_mul_f32_e32 v27, v27, v34
	v_mul_f32_e32 v12, v12, v34
	v_mul_f32_e32 v28, v28, v34
	v_mul_f32_e32 v13, v13, v34
	v_mul_f32_e32 v29, v29, v34
	v_mul_f32_e32 v14, v14, v34
	v_mul_f32_e32 v30, v30, v34
	v_mul_f32_e32 v15, v15, v34
	v_mul_f32_e32 v31, v31, v34
	v_cvt_pk_fp8_f32 v36, v0, v1
	v_cvt_pk_fp8_f32 v36, v2, v3 op_sel:[0,0,1]
	v_cvt_pk_fp8_f32 v37, v4, v5
	v_cvt_pk_fp8_f32 v37, v6, v7 op_sel:[0,0,1]
	v_cvt_pk_fp8_f32 v38, v8, v9
	v_cvt_pk_fp8_f32 v38, v10, v11 op_sel:[0,0,1]
	v_cvt_pk_fp8_f32 v39, v12, v13
	v_cvt_pk_fp8_f32 v39, v14, v15 op_sel:[0,0,1]
	v_cvt_pk_fp8_f32 v40, v16, v17
	v_cvt_pk_fp8_f32 v40, v18, v19 op_sel:[0,0,1]
	v_cvt_pk_fp8_f32 v41, v20, v21
	v_cvt_pk_fp8_f32 v41, v22, v23 op_sel:[0,0,1]
	ds_write2_b32 v231, v36, v37 offset1:2
	ds_write2_b32 v231, v38, v39 offset0:4 offset1:6
	ds_write2_b32 v231, v40, v41 offset0:8 offset1:10
	v_cvt_pk_fp8_f32 v42, v24, v25
	v_cvt_pk_fp8_f32 v42, v26, v27 op_sel:[0,0,1]
	v_cvt_pk_fp8_f32 v43, v28, v29
	v_cvt_pk_fp8_f32 v43, v30, v31 op_sel:[0,0,1]
	v_lshlrev_b32_e32 v0, 13, v196
	v_cndmask_b32_e64 v1, 0, v236, s[80:81]
	v_or3_b32 v0, v0, v1, v194
	ds_bpermute_b32 v13, v239, v0
	ds_write2_b32 v231, v42, v43 offset0:12 offset1:14
	s_waitcnt lgkmcnt(0)
	v_mov_b32_e32 v14, s19
	v_log_f32_e32 v33, v33
	s_waitcnt lgkmcnt(1)
	v_lshrrev_b32_e32 v8, 13, v13
	v_and_b32_e32 v11, 3, v8
	v_lshlrev_b32_e32 v162, 25, v11
	v_and_b32_e32 v10, 0x1fff, v13
	v_lshl_add_u64 v[8:9], s[28:29], 0, v[162:163]
	v_cmp_eq_u32_e32 vcc, 3, v11
	v_mov_b32_e32 v11, s18
	v_or_b32_e32 v10, s10, v10
	v_cndmask_b32_e32 v8, v8, v11, vcc
	v_mov_b32_e32 v11, s11
	ds_read_b128 v[0:3], v237
	ds_read_b128 v[4:7], v237 offset:16
	v_cndmask_b32_e32 v9, v9, v14, vcc
	v_lshlrev_b64 v[10:11], 10, v[10:11]
	v_lshl_add_u64 v[8:9], v[8:9], 0, v[10:11]
	v_lshl_add_u64 v[8:9], v[8:9], 0, s[72:73]
	v_and_b32_e32 v10, 0x8000, v13
	v_lshl_add_u64 v[8:9], v[8:9], 0, v[172:173]
	v_cmp_eq_u32_e32 vcc, 0, v10
	v_add_f32_e32 v12, v197, v33
	v_mov_b32_e32 v197, v163
	v_cndmask_b32_e32 v9, v9, v175, vcc
	v_cndmask_b32_e32 v8, v8, v174, vcc
	s_waitcnt lgkmcnt(1)
	global_store_dwordx4 v[8:9], v[0:3], off nt
	s_waitcnt lgkmcnt(0)
	global_store_dwordx4 v[8:9], v[4:7], off offset:16 nt
	v_ashrrev_i32_e32 v195, 31, v194
	v_lshlrev_b64 v[0:1], 15, v[196:197]
	v_lshl_add_u64 v[0:1], v[0:1], 0, s[10:11]
	v_lshl_add_u64 v[0:1], v[0:1], 0, v[194:195]
	v_lshlrev_b64 v[0:1], 6, v[0:1]
	v_lshl_add_u64 v[0:1], s[76:77], 0, v[0:1]
	v_cndmask_b32_e64 v1, v177, v1, s[80:81]
	v_cndmask_b32_e64 v0, v176, v0, s[80:81]
	s_and_b64 vcc, exec, s[84:85]
	global_store_dword v[0:1], v12, off nt
	s_cbranch_vccnz .LBB0_407
	s_waitcnt vmcnt(6)
	v_mov_b64_e32 v[108:109], v[124:125]
	s_waitcnt vmcnt(5)
	v_mov_b64_e32 v[104:105], v[120:121]
	s_waitcnt vmcnt(4)
	v_mov_b64_e32 v[100:101], v[116:117]
	s_waitcnt vmcnt(3)
	v_mov_b64_e32 v[96:97], v[112:113]
	s_mov_b64 s[80:81], s[82:83]
	v_mov_b64_e32 v[110:111], v[126:127]
	v_mov_b64_e32 v[106:107], v[122:123]
	v_mov_b64_e32 v[102:103], v[118:119]
	v_mov_b64_e32 v[98:99], v[114:115]
	v_mov_b32_e32 v196, v32
	v_mov_b32_e32 v194, v242
	s_mov_b32 s58, s8
	v_mov_b32_e32 v195, v243
	s_mov_b64 s[82:83], s[86:87]
	s_branch .LBB0_387
